# v31 + kt/ssm_a tasks moved to the blocks that get one GEMM tile fewer in P1/P2 (two tasks each, G==256 only)
# baseline (speedup 1.0000x reference)
; __device__ __forceinline__ void ssm_kt_task(unsigned char* ws, LAS unsigned char* lds, int l, int task, int tid) {
;     ...
;     for (int r = 0; r < 4; ++r) { const int c = r * 512 + tid, s = c & 15, n = (c >> 4) & 63, dir = c >> 10; const int d = lb * 16 + s - 63;
;         const bool ok = dir == 0 ? (d >= 0) : (d <= 0); const int e = d < 0 ? -d : d;
;         f32x2 v = (f32x2){0.f, 0.f}; if (ok && e <= 64) v = ptab[(size_t)((g * 2 + dir) * NS + n) * 65 + e];
;         Pl[c] = v; }
; __global__ void __launch_bounds__(NTHREADS) mega_fwd(Params P) {
;     ...
;             for (int rep_ = 0; rep_ < PROBE_MISC_REPS; ++rep_) { ssm_tables(ws, l, tid); for (int t = vcu; t < NG * 8; t += G) ssm_kt_task(ws, lds, l, t, tid); __syncthreads(); }
.LBB0_274:
	s_movk_i32 s52, 0x208
	s_or_b64 exec, exec, s[34:35]
	s_mov_b32 s100, s76
	s_movk_i32 s101, 0xff
	s_cmpk_lg_i32 s76, 0x100
	s_cbranch_scc1 .Lkt_rb_go
	s_mov_b32 s100, 1
	s_and_b32 s101, s16, 31
	s_cmpk_lt_i32 s101, 16
	s_cbranch_scc1 .Lkt_rb_none
	s_andn2_b32 s16, s16, 31
	s_sub_i32 s101, s101, 16
	s_lshl_b32 s101, s101, 1
	s_add_i32 s16, s16, s101
	s_add_i32 s101, s16, 1
	s_branch .Lkt_rb_go
.Lkt_rb_none:
	s_movk_i32 s16, 0x100
	s_movk_i32 s101, 0xff
.Lkt_rb_go:
	s_cmp_gt_i32 s16, s101
	s_cbranch_scc1 .LBB0_308
	v_lshrrev_b32_e32 v0, 4, v4
	v_ashrrev_i32_e32 v1, 4, v4
	s_movk_i32 s6, 0xffc0
	s_movk_i32 s7, 0x400
	s_waitcnt vmcnt(4)
	v_bfi_b32 v17, s6, v1, v0
	v_add_u32_e32 v1, 0x200, v4
	v_cmp_gt_u32_e64 s[36:37], s7, v1
	v_lshrrev_b32_e32 v2, 4, v1
	v_ashrrev_i32_e32 v1, 4, v1
	s_waitcnt vmcnt(1)
	v_bfi_b32 v39, s6, v1, v2
	v_add_u32_e32 v1, 0x400, v4
	v_ashrrev_i32_e32 v1, 4, v1
	v_bfi_b32 v40, s6, v1, v0
	v_add_u32_e32 v0, 0x600, v4
	v_cmp_gt_u32_e64 s[40:41], s7, v0
	v_lshrrev_b32_e32 v1, 4, v0
	v_ashrrev_i32_e32 v0, 4, v0
	v_cmp_gt_u32_e64 s[34:35], s7, v4
	v_bfi_b32 v41, s6, v0, v1
	v_bfe_u32 v0, v4, 4, 4
	v_readlane_b32 s6, v251, 34
	v_and_b32_e32 v16, 15, v5
	v_lshlrev_b32_e32 v184, 5, v0
	v_readlane_b32 s7, v251, 35
	v_lshlrev_b32_e32 v44, 6, v0
	v_ashrrev_i32_e32 v2, 5, v4
	v_lshl_add_u64 v[0:1], s[6:7], 0, v[184:185]
	v_lshlrev_b32_e32 v184, 1, v16
	v_readlane_b32 s6, v255, 40
	v_lshl_add_u64 v[18:19], v[0:1], 0, v[184:185]
	v_lshlrev_b32_e32 v184, 3, v16
	v_readlane_b32 s7, v255, 41
	s_movk_i32 s3, 0xfbff
	v_lshlrev_b32_e32 v0, 3, v2
	v_lshl_add_u64 v[20:21], s[6:7], 0, v[184:185]
	v_readlane_b32 s6, v255, 42
	v_cmp_lt_u32_e64 s[38:39], s3, v4
	v_and_b32_e32 v42, -8, v2
	v_and_b32_e32 v0, 0xffffffc0, v0
	v_readlane_b32 s3, v255, 56
	v_readlane_b32 s7, v255, 43
	v_lshl_add_u32 v38, v4, 3, 0
	v_lshl_add_u32 v43, v42, 3, 0
	v_add_u32_e32 v45, s3, v0
	v_lshl_add_u64 v[22:23], s[6:7], 0, v[184:185]
	s_movk_i32 s7, 0x7fff
	s_movk_i32 s6, 0x7f
	s_branch .LBB0_277
.LBB0_276:
	s_or_b64 exec, exec, s[44:45]
	s_add_i32 s16, s16, s100
	s_cmp_gt_i32 s16, s101
	s_barrier
	s_cbranch_scc1 .LBB0_308

; __device__ __forceinline__ int opaque_tid(int wv) { asm volatile("" : "+s"(wv)); return wv * 64 + lane_id_asm(); }
; __device__ __forceinline__ void ssm_a_task(unsigned char* ws, LAS unsigned char* lds, int task, int tid) {
;     const int lane = tid & 63, wid = tid >> 6, rr = lane & 15, kk = lane >> 4;
;     const int g = task >> 3, cb = task & 7;
;     f32x4 acc[2][4];
; #pragma unroll
;     for (int a = 0; a < 2; ++a)
; #pragma unroll
;         for (int c = 0; c < 4; ++c) acc[a][c] = (f32x4){0.f, 0.f, 0.f, 0.f};
;     const bf16* WA = (const bf16*)(ws + WS_WA) + ((size_t)(g * 256 + wid * 32 + rr) * 1024 + 8 * kk);
; __global__ void __launch_bounds__(NTHREADS) mega_fwd(Params P) {
;     ...
;             { const int tid2 = opaque_tid(wv); for (int rep_ = 0; rep_ < PROBE_MISC_REPS; ++rep_) for (int t = vcu; t < NG * 8; t += G) ssm_a_task(ws, lds, t, tid2); }
.LBB0_601:
	s_mov_b32 s3, s77
	s_mov_b32 s100, s76
	s_movk_i32 s101, 0xff
	s_cmpk_lg_i32 s76, 0x100
	s_cbranch_scc1 .Lssma_rb_go
	s_mov_b32 s100, 1
	s_and_b32 s101, s54, 31
	s_cmpk_lt_i32 s101, 16
	s_cbranch_scc1 .Lssma_rb_none
	s_andn2_b32 s54, s54, 31
	s_sub_i32 s101, s101, 16
	s_lshl_b32 s101, s101, 1
	s_add_i32 s54, s54, s101
	s_add_i32 s101, s54, 1
	s_branch .Lssma_rb_go
.Lssma_rb_none:
	s_movk_i32 s54, 0x100
	s_movk_i32 s101, 0xff
.Lssma_rb_go:
	s_cmp_gt_i32 s54, s101
	s_barrier
	v_mbcnt_lo_u32_b32 v0, -1, 0
	v_mbcnt_hi_u32_b32 v0, -1, v0
	s_cbranch_scc1 .LBB0_608
	v_lshl_add_u32 v44, s3, 6, v0
	v_ashrrev_i32_e32 v2, 1, v44
	v_and_b32_e32 v2, 0xffffffe0, v2
	v_readlane_b32 s6, v253, 63
	v_ashrrev_i32_e32 v3, 31, v2
	v_readlane_b32 s7, v254, 0
	v_and_b32_e32 v1, 15, v0
	v_and_b32_e32 v6, 16, v0
	v_lshl_add_u64 v[4:5], v[2:3], 2, s[6:7]
	v_readlane_b32 s6, v255, 46
	v_and_b32_e32 v184, 48, v0
	v_readlane_b32 s7, v255, 47
	v_lshlrev_b32_e32 v0, 6, v0
	v_lshlrev_b32_e32 v45, 5, v1
	v_lshl_add_u64 v[34:35], s[6:7], 0, v[184:185]
	v_and_b32_e32 v0, 0x800, v0
	v_readlane_b32 s6, v255, 48
	v_or3_b32 v0, v0, v45, v6
	v_readlane_b32 s7, v255, 49
	v_lshl_add_u64 v[32:33], v[4:5], 0, v[184:185]
	v_or_b32_e32 v46, v2, v1
	v_add_u32_e32 v47, 0, v0
	v_lshl_add_u64 v[36:37], s[6:7], 0, v[184:185]

; #define LAS __attribute__((address_space(3)))
; __device__ __forceinline__ void ssm_a_task(unsigned char* ws, LAS unsigned char* lds, int task, int tid) {
;     ...
;         for (int ks = 0; ks < 16; ++ks) {
;             bf16x8 bfr[4], afr[2];
; #pragma unroll
;             for (int a = 0; a < 2; ++a) afr[a] = *(const bf16x8*)(WA + (size_t)a * 16 * 1024 + (hh * 16 + ks) * 32);
; #pragma unroll
;             for (int c = 0; c < 4; ++c) bfr[c] = *(const LAS bf16x8*)(lds + SS_UB + (((2 * ks + (kk >> 1)) * 64 + c * 16 + rr) * 32 + (kk & 1) * 16));
; #pragma unroll
;             for (int a = 0; a < 2; ++a)
; #pragma unroll
;                 for (int c = 0; c < 4; ++c) acc[a][c] = __builtin_amdgcn_mfma_f32_16x16x32_bf16(afr[a], bfr[c], acc[a][c], 0, 0, 0);
;         }
.LBB0_606:
	v_add_co_u32_e32 v164, vcc, 0xffff8000, v38
	s_nop 1
	v_addc_co_u32_e32 v165, vcc, -1, v39, vcc
	v_add_u32_e32 v166, 0x10000, v47
	global_load_dwordx4 v[100:103], v[38:39], off offset:-192
	global_load_dwordx4 v[104:107], v[164:165], off offset:-192
	global_load_dwordx4 v[108:111], v[38:39], off offset:-128
	global_load_dwordx4 v[112:115], v[164:165], off offset:-128
	global_load_dwordx4 v[116:119], v[38:39], off offset:-64
	global_load_dwordx4 v[120:123], v[164:165], off offset:-64
	global_load_dwordx4 v[124:127], v[38:39], off offset:0
	global_load_dwordx4 v[128:131], v[164:165], off offset:0
	ds_read_b128 v[132:135], v166 offset:0
	ds_read_b128 v[136:139], v166 offset:512
	ds_read_b128 v[140:143], v166 offset:1024
	ds_read_b128 v[144:147], v166 offset:1536
	ds_read_b128 v[148:151], v166 offset:4096
	ds_read_b128 v[152:155], v166 offset:4608
	ds_read_b128 v[156:159], v166 offset:5120
	ds_read_b128 v[160:163], v166 offset:5632
	s_waitcnt lgkmcnt(4)
	s_waitcnt vmcnt(7)
	v_mfma_f32_16x16x32_bf16 v[12:15], v[100:103], v[132:135], v[12:15]
	v_mfma_f32_16x16x32_bf16 v[8:11], v[100:103], v[136:139], v[8:11]
	v_mfma_f32_16x16x32_bf16 v[4:7], v[100:103], v[140:143], v[4:7]
	v_mfma_f32_16x16x32_bf16 v[0:3], v[100:103], v[144:147], v[0:3]
	s_waitcnt vmcnt(6)
	v_mfma_f32_16x16x32_bf16 v[28:31], v[104:107], v[132:135], v[28:31]
	v_mfma_f32_16x16x32_bf16 v[24:27], v[104:107], v[136:139], v[24:27]
	v_mfma_f32_16x16x32_bf16 v[20:23], v[104:107], v[140:143], v[20:23]
	v_mfma_f32_16x16x32_bf16 v[16:19], v[104:107], v[144:147], v[16:19]
	global_load_dwordx4 v[100:103], v[38:39], off offset:64
	global_load_dwordx4 v[104:107], v[164:165], off offset:64
	ds_read_b128 v[132:135], v166 offset:8192
	ds_read_b128 v[136:139], v166 offset:8704
	ds_read_b128 v[140:143], v166 offset:9216
	ds_read_b128 v[144:147], v166 offset:9728
	s_waitcnt lgkmcnt(4)
	s_waitcnt vmcnt(7)
	v_mfma_f32_16x16x32_bf16 v[12:15], v[108:111], v[148:151], v[12:15]
	v_mfma_f32_16x16x32_bf16 v[8:11], v[108:111], v[152:155], v[8:11]
	v_mfma_f32_16x16x32_bf16 v[4:7], v[108:111], v[156:159], v[4:7]
	v_mfma_f32_16x16x32_bf16 v[0:3], v[108:111], v[160:163], v[0:3]
	s_waitcnt vmcnt(6)
	v_mfma_f32_16x16x32_bf16 v[28:31], v[112:115], v[148:151], v[28:31]
	v_mfma_f32_16x16x32_bf16 v[24:27], v[112:115], v[152:155], v[24:27]
	v_mfma_f32_16x16x32_bf16 v[20:23], v[112:115], v[156:159], v[20:23]
	v_mfma_f32_16x16x32_bf16 v[16:19], v[112:115], v[160:163], v[16:19]
	global_load_dwordx4 v[108:111], v[38:39], off offset:128
	global_load_dwordx4 v[112:115], v[164:165], off offset:128
	ds_read_b128 v[148:151], v166 offset:12288
	ds_read_b128 v[152:155], v166 offset:12800
	ds_read_b128 v[156:159], v166 offset:13312
	ds_read_b128 v[160:163], v166 offset:13824
	s_waitcnt lgkmcnt(4)
	s_waitcnt vmcnt(7)
	v_mfma_f32_16x16x32_bf16 v[12:15], v[116:119], v[132:135], v[12:15]
	v_mfma_f32_16x16x32_bf16 v[8:11], v[116:119], v[136:139], v[8:11]
	v_mfma_f32_16x16x32_bf16 v[4:7], v[116:119], v[140:143], v[4:7]
	v_mfma_f32_16x16x32_bf16 v[0:3], v[116:119], v[144:147], v[0:3]
	s_waitcnt vmcnt(6)
	v_mfma_f32_16x16x32_bf16 v[28:31], v[120:123], v[132:135], v[28:31]
	v_mfma_f32_16x16x32_bf16 v[24:27], v[120:123], v[136:139], v[24:27]
	v_mfma_f32_16x16x32_bf16 v[20:23], v[120:123], v[140:143], v[20:23]
	v_mfma_f32_16x16x32_bf16 v[16:19], v[120:123], v[144:147], v[16:19]
	global_load_dwordx4 v[116:119], v[38:39], off offset:192
	global_load_dwordx4 v[120:123], v[164:165], off offset:192
	ds_read_b128 v[132:135], v166 offset:16384
	ds_read_b128 v[136:139], v166 offset:16896
	ds_read_b128 v[140:143], v166 offset:17408
	ds_read_b128 v[144:147], v166 offset:17920
	s_waitcnt lgkmcnt(4)
	s_waitcnt vmcnt(7)
	v_mfma_f32_16x16x32_bf16 v[12:15], v[124:127], v[148:151], v[12:15]
	v_mfma_f32_16x16x32_bf16 v[8:11], v[124:127], v[152:155], v[8:11]
	v_mfma_f32_16x16x32_bf16 v[4:7], v[124:127], v[156:159], v[4:7]
	v_mfma_f32_16x16x32_bf16 v[0:3], v[124:127], v[160:163], v[0:3]
	s_waitcnt vmcnt(6)
	v_mfma_f32_16x16x32_bf16 v[28:31], v[128:131], v[148:151], v[28:31]
	v_mfma_f32_16x16x32_bf16 v[24:27], v[128:131], v[152:155], v[24:27]
	v_mfma_f32_16x16x32_bf16 v[20:23], v[128:131], v[156:159], v[20:23]
	v_mfma_f32_16x16x32_bf16 v[16:19], v[128:131], v[160:163], v[16:19]
	global_load_dwordx4 v[124:127], v[38:39], off offset:256
	global_load_dwordx4 v[128:131], v[164:165], off offset:256
	ds_read_b128 v[148:151], v166 offset:20480
	ds_read_b128 v[152:155], v166 offset:20992
	ds_read_b128 v[156:159], v166 offset:21504
	ds_read_b128 v[160:163], v166 offset:22016
	s_waitcnt lgkmcnt(4)
	s_waitcnt vmcnt(7)
	v_mfma_f32_16x16x32_bf16 v[12:15], v[100:103], v[132:135], v[12:15]
	v_mfma_f32_16x16x32_bf16 v[8:11], v[100:103], v[136:139], v[8:11]
	v_mfma_f32_16x16x32_bf16 v[4:7], v[100:103], v[140:143], v[4:7]
	v_mfma_f32_16x16x32_bf16 v[0:3], v[100:103], v[144:147], v[0:3]
	s_waitcnt vmcnt(6)
	v_mfma_f32_16x16x32_bf16 v[28:31], v[104:107], v[132:135], v[28:31]
	v_mfma_f32_16x16x32_bf16 v[24:27], v[104:107], v[136:139], v[24:27]
	v_mfma_f32_16x16x32_bf16 v[20:23], v[104:107], v[140:143], v[20:23]
	v_mfma_f32_16x16x32_bf16 v[16:19], v[104:107], v[144:147], v[16:19]
	global_load_dwordx4 v[100:103], v[38:39], off offset:320
	global_load_dwordx4 v[104:107], v[164:165], off offset:320
	ds_read_b128 v[132:135], v166 offset:24576
	ds_read_b128 v[136:139], v166 offset:25088
	ds_read_b128 v[140:143], v166 offset:25600
	ds_read_b128 v[144:147], v166 offset:26112
	s_waitcnt lgkmcnt(4)
	s_waitcnt vmcnt(7)
	v_mfma_f32_16x16x32_bf16 v[12:15], v[108:111], v[148:151], v[12:15]
	v_mfma_f32_16x16x32_bf16 v[8:11], v[108:111], v[152:155], v[8:11]
	v_mfma_f32_16x16x32_bf16 v[4:7], v[108:111], v[156:159], v[4:7]
	v_mfma_f32_16x16x32_bf16 v[0:3], v[108:111], v[160:163], v[0:3]
	s_waitcnt vmcnt(6)
; #define LAS __attribute__((address_space(3)))
; __device__ __forceinline__ void ssm_a_task(unsigned char* ws, LAS unsigned char* lds, int task, int tid) {
;     ...
;         for (int ks = 0; ks < 16; ++ks) {
;             bf16x8 bfr[4], afr[2];
; #pragma unroll
;             for (int a = 0; a < 2; ++a) afr[a] = *(const bf16x8*)(WA + (size_t)a * 16 * 1024 + (hh * 16 + ks) * 32);
; #pragma unroll
;             for (int c = 0; c < 4; ++c) bfr[c] = *(const LAS bf16x8*)(lds + SS_UB + (((2 * ks + (kk >> 1)) * 64 + c * 16 + rr) * 32 + (kk & 1) * 16));
; #pragma unroll
;             for (int a = 0; a < 2; ++a)
; #pragma unroll
;                 for (int c = 0; c < 4; ++c) acc[a][c] = __builtin_amdgcn_mfma_f32_16x16x32_bf16(afr[a], bfr[c], acc[a][c], 0, 0, 0);
;         }
	v_mfma_f32_16x16x32_bf16 v[28:31], v[112:115], v[148:151], v[28:31]
	v_mfma_f32_16x16x32_bf16 v[24:27], v[112:115], v[152:155], v[24:27]
	v_mfma_f32_16x16x32_bf16 v[20:23], v[112:115], v[156:159], v[20:23]
	v_mfma_f32_16x16x32_bf16 v[16:19], v[112:115], v[160:163], v[16:19]
	global_load_dwordx4 v[108:111], v[38:39], off offset:384
	global_load_dwordx4 v[112:115], v[164:165], off offset:384
	ds_read_b128 v[148:151], v166 offset:28672
	ds_read_b128 v[152:155], v166 offset:29184
	ds_read_b128 v[156:159], v166 offset:29696
	ds_read_b128 v[160:163], v166 offset:30208
	s_waitcnt lgkmcnt(4)
	s_waitcnt vmcnt(7)
	v_mfma_f32_16x16x32_bf16 v[12:15], v[116:119], v[132:135], v[12:15]
	v_mfma_f32_16x16x32_bf16 v[8:11], v[116:119], v[136:139], v[8:11]
	v_mfma_f32_16x16x32_bf16 v[4:7], v[116:119], v[140:143], v[4:7]
	v_mfma_f32_16x16x32_bf16 v[0:3], v[116:119], v[144:147], v[0:3]
	s_waitcnt vmcnt(6)
	v_mfma_f32_16x16x32_bf16 v[28:31], v[120:123], v[132:135], v[28:31]
	v_mfma_f32_16x16x32_bf16 v[24:27], v[120:123], v[136:139], v[24:27]
	v_mfma_f32_16x16x32_bf16 v[20:23], v[120:123], v[140:143], v[20:23]
	v_mfma_f32_16x16x32_bf16 v[16:19], v[120:123], v[144:147], v[16:19]
	global_load_dwordx4 v[116:119], v[38:39], off offset:448
	global_load_dwordx4 v[120:123], v[164:165], off offset:448
	ds_read_b128 v[132:135], v166 offset:32768
	ds_read_b128 v[136:139], v166 offset:33280
	ds_read_b128 v[140:143], v166 offset:33792
	ds_read_b128 v[144:147], v166 offset:34304
	s_waitcnt lgkmcnt(4)
	s_waitcnt vmcnt(7)
	v_mfma_f32_16x16x32_bf16 v[12:15], v[124:127], v[148:151], v[12:15]
	v_mfma_f32_16x16x32_bf16 v[8:11], v[124:127], v[152:155], v[8:11]
	v_mfma_f32_16x16x32_bf16 v[4:7], v[124:127], v[156:159], v[4:7]
	v_mfma_f32_16x16x32_bf16 v[0:3], v[124:127], v[160:163], v[0:3]
	s_waitcnt vmcnt(6)
	v_mfma_f32_16x16x32_bf16 v[28:31], v[128:131], v[148:151], v[28:31]
	v_mfma_f32_16x16x32_bf16 v[24:27], v[128:131], v[152:155], v[24:27]
	v_mfma_f32_16x16x32_bf16 v[20:23], v[128:131], v[156:159], v[20:23]
	v_mfma_f32_16x16x32_bf16 v[16:19], v[128:131], v[160:163], v[16:19]
	global_load_dwordx4 v[124:127], v[38:39], off offset:512
	global_load_dwordx4 v[128:131], v[164:165], off offset:512
	ds_read_b128 v[148:151], v166 offset:36864
	ds_read_b128 v[152:155], v166 offset:37376
	ds_read_b128 v[156:159], v166 offset:37888
	ds_read_b128 v[160:163], v166 offset:38400
	s_waitcnt lgkmcnt(4)
	s_waitcnt vmcnt(7)
	v_mfma_f32_16x16x32_bf16 v[12:15], v[100:103], v[132:135], v[12:15]
	v_mfma_f32_16x16x32_bf16 v[8:11], v[100:103], v[136:139], v[8:11]
	v_mfma_f32_16x16x32_bf16 v[4:7], v[100:103], v[140:143], v[4:7]
	v_mfma_f32_16x16x32_bf16 v[0:3], v[100:103], v[144:147], v[0:3]
	s_waitcnt vmcnt(6)
	v_mfma_f32_16x16x32_bf16 v[28:31], v[104:107], v[132:135], v[28:31]
	v_mfma_f32_16x16x32_bf16 v[24:27], v[104:107], v[136:139], v[24:27]
	v_mfma_f32_16x16x32_bf16 v[20:23], v[104:107], v[140:143], v[20:23]
	v_mfma_f32_16x16x32_bf16 v[16:19], v[104:107], v[144:147], v[16:19]
	global_load_dwordx4 v[100:103], v[38:39], off offset:576
	global_load_dwordx4 v[104:107], v[164:165], off offset:576
	ds_read_b128 v[132:135], v166 offset:40960
	ds_read_b128 v[136:139], v166 offset:41472
	ds_read_b128 v[140:143], v166 offset:41984
	ds_read_b128 v[144:147], v166 offset:42496
	s_waitcnt lgkmcnt(4)
	s_waitcnt vmcnt(7)
	v_mfma_f32_16x16x32_bf16 v[12:15], v[108:111], v[148:151], v[12:15]
	v_mfma_f32_16x16x32_bf16 v[8:11], v[108:111], v[152:155], v[8:11]
	v_mfma_f32_16x16x32_bf16 v[4:7], v[108:111], v[156:159], v[4:7]
	v_mfma_f32_16x16x32_bf16 v[0:3], v[108:111], v[160:163], v[0:3]
	s_waitcnt vmcnt(6)
	v_mfma_f32_16x16x32_bf16 v[28:31], v[112:115], v[148:151], v[28:31]
	v_mfma_f32_16x16x32_bf16 v[24:27], v[112:115], v[152:155], v[24:27]
	v_mfma_f32_16x16x32_bf16 v[20:23], v[112:115], v[156:159], v[20:23]
	v_mfma_f32_16x16x32_bf16 v[16:19], v[112:115], v[160:163], v[16:19]
	global_load_dwordx4 v[108:111], v[38:39], off offset:640
	global_load_dwordx4 v[112:115], v[164:165], off offset:640
	ds_read_b128 v[148:151], v166 offset:45056
	ds_read_b128 v[152:155], v166 offset:45568
	ds_read_b128 v[156:159], v166 offset:46080
	ds_read_b128 v[160:163], v166 offset:46592
	s_waitcnt lgkmcnt(4)
	s_waitcnt vmcnt(7)
	v_mfma_f32_16x16x32_bf16 v[12:15], v[116:119], v[132:135], v[12:15]
	v_mfma_f32_16x16x32_bf16 v[8:11], v[116:119], v[136:139], v[8:11]
	v_mfma_f32_16x16x32_bf16 v[4:7], v[116:119], v[140:143], v[4:7]
	v_mfma_f32_16x16x32_bf16 v[0:3], v[116:119], v[144:147], v[0:3]
	s_waitcnt vmcnt(6)
	v_mfma_f32_16x16x32_bf16 v[28:31], v[120:123], v[132:135], v[28:31]
	v_mfma_f32_16x16x32_bf16 v[24:27], v[120:123], v[136:139], v[24:27]
	v_mfma_f32_16x16x32_bf16 v[20:23], v[120:123], v[140:143], v[20:23]
	v_mfma_f32_16x16x32_bf16 v[16:19], v[120:123], v[144:147], v[16:19]
	global_load_dwordx4 v[116:119], v[38:39], off offset:704
	global_load_dwordx4 v[120:123], v[164:165], off offset:704
	ds_read_b128 v[132:135], v166 offset:49152
	ds_read_b128 v[136:139], v166 offset:49664
	ds_read_b128 v[140:143], v166 offset:50176
	ds_read_b128 v[144:147], v166 offset:50688
	s_waitcnt lgkmcnt(4)
; __device__ __forceinline__ int opaque_tid(int wv) { asm volatile("" : "+s"(wv)); return wv * 64 + lane_id_asm(); }
; __device__ __forceinline__ void ssm_a_task(unsigned char* ws, LAS unsigned char* lds, int task, int tid) {
;     ...
;             for (int a = 0; a < 2; ++a)
; #pragma unroll
;                 for (int c = 0; c < 4; ++c) acc[a][c] = __builtin_amdgcn_mfma_f32_16x16x32_bf16(afr[a], bfr[c], acc[a][c], 0, 0, 0);
;         }
;         __syncthreads();
;     }
;     float* S = (float*)(ws + AR_S);
; #pragma unroll
;     for (int a = 0; a < 2; ++a)
; #pragma unroll
;         for (int c = 0; c < 4; ++c) { const int col = cb * 64 + c * 16 + rr; *(f32x4*)(S + ((size_t)(col * NG + g) * 256 + wid * 32 + a * 16 + 4 * kk)) = acc[a][c]; }
; __global__ void __launch_bounds__(NTHREADS) mega_fwd(Params P) {
;     ...
;             { const int tid2 = opaque_tid(wv); for (int rep_ = 0; rep_ < PROBE_MISC_REPS; ++rep_) for (int t = vcu; t < NG * 8; t += G) ssm_a_task(ws, lds, t, tid2); }
	s_waitcnt vmcnt(7)
	v_mfma_f32_16x16x32_bf16 v[12:15], v[124:127], v[148:151], v[12:15]
	v_mfma_f32_16x16x32_bf16 v[8:11], v[124:127], v[152:155], v[8:11]
	v_mfma_f32_16x16x32_bf16 v[4:7], v[124:127], v[156:159], v[4:7]
	v_mfma_f32_16x16x32_bf16 v[0:3], v[124:127], v[160:163], v[0:3]
	s_waitcnt vmcnt(6)
	v_mfma_f32_16x16x32_bf16 v[28:31], v[128:131], v[148:151], v[28:31]
	v_mfma_f32_16x16x32_bf16 v[24:27], v[128:131], v[152:155], v[24:27]
	v_mfma_f32_16x16x32_bf16 v[20:23], v[128:131], v[156:159], v[20:23]
	v_mfma_f32_16x16x32_bf16 v[16:19], v[128:131], v[160:163], v[16:19]
	global_load_dwordx4 v[124:127], v[38:39], off offset:768
	global_load_dwordx4 v[128:131], v[164:165], off offset:768
	ds_read_b128 v[148:151], v166 offset:53248
	ds_read_b128 v[152:155], v166 offset:53760
	ds_read_b128 v[156:159], v166 offset:54272
	ds_read_b128 v[160:163], v166 offset:54784
	s_waitcnt lgkmcnt(4)
	s_waitcnt vmcnt(7)
	v_mfma_f32_16x16x32_bf16 v[12:15], v[100:103], v[132:135], v[12:15]
	v_mfma_f32_16x16x32_bf16 v[8:11], v[100:103], v[136:139], v[8:11]
	v_mfma_f32_16x16x32_bf16 v[4:7], v[100:103], v[140:143], v[4:7]
	v_mfma_f32_16x16x32_bf16 v[0:3], v[100:103], v[144:147], v[0:3]
	s_waitcnt vmcnt(6)
	v_mfma_f32_16x16x32_bf16 v[28:31], v[104:107], v[132:135], v[28:31]
	v_mfma_f32_16x16x32_bf16 v[24:27], v[104:107], v[136:139], v[24:27]
	v_mfma_f32_16x16x32_bf16 v[20:23], v[104:107], v[140:143], v[20:23]
	v_mfma_f32_16x16x32_bf16 v[16:19], v[104:107], v[144:147], v[16:19]
	ds_read_b128 v[132:135], v166 offset:57344
	ds_read_b128 v[136:139], v166 offset:57856
	ds_read_b128 v[140:143], v166 offset:58368
	ds_read_b128 v[144:147], v166 offset:58880
	s_waitcnt lgkmcnt(4)
	s_waitcnt vmcnt(5)
	v_mfma_f32_16x16x32_bf16 v[12:15], v[108:111], v[148:151], v[12:15]
	v_mfma_f32_16x16x32_bf16 v[8:11], v[108:111], v[152:155], v[8:11]
	v_mfma_f32_16x16x32_bf16 v[4:7], v[108:111], v[156:159], v[4:7]
	v_mfma_f32_16x16x32_bf16 v[0:3], v[108:111], v[160:163], v[0:3]
	s_waitcnt vmcnt(4)
	v_mfma_f32_16x16x32_bf16 v[28:31], v[112:115], v[148:151], v[28:31]
	v_mfma_f32_16x16x32_bf16 v[24:27], v[112:115], v[152:155], v[24:27]
	v_mfma_f32_16x16x32_bf16 v[20:23], v[112:115], v[156:159], v[20:23]
	v_mfma_f32_16x16x32_bf16 v[16:19], v[112:115], v[160:163], v[16:19]
	ds_read_b128 v[148:151], v166 offset:61440
	ds_read_b128 v[152:155], v166 offset:61952
	ds_read_b128 v[156:159], v166 offset:62464
	ds_read_b128 v[160:163], v166 offset:62976
	s_waitcnt lgkmcnt(4)
	s_waitcnt vmcnt(3)
	v_mfma_f32_16x16x32_bf16 v[12:15], v[116:119], v[132:135], v[12:15]
	v_mfma_f32_16x16x32_bf16 v[8:11], v[116:119], v[136:139], v[8:11]
	v_mfma_f32_16x16x32_bf16 v[4:7], v[116:119], v[140:143], v[4:7]
	v_mfma_f32_16x16x32_bf16 v[0:3], v[116:119], v[144:147], v[0:3]
	s_waitcnt vmcnt(2)
	v_mfma_f32_16x16x32_bf16 v[28:31], v[120:123], v[132:135], v[28:31]
	v_mfma_f32_16x16x32_bf16 v[24:27], v[120:123], v[136:139], v[24:27]
	v_mfma_f32_16x16x32_bf16 v[20:23], v[120:123], v[140:143], v[20:23]
	v_mfma_f32_16x16x32_bf16 v[16:19], v[120:123], v[144:147], v[16:19]
	s_waitcnt lgkmcnt(0)
	s_waitcnt vmcnt(1)
	v_mfma_f32_16x16x32_bf16 v[12:15], v[124:127], v[148:151], v[12:15]
	v_mfma_f32_16x16x32_bf16 v[8:11], v[124:127], v[152:155], v[8:11]
	v_mfma_f32_16x16x32_bf16 v[4:7], v[124:127], v[156:159], v[4:7]
	v_mfma_f32_16x16x32_bf16 v[0:3], v[124:127], v[160:163], v[0:3]
	s_waitcnt vmcnt(0)
	v_mfma_f32_16x16x32_bf16 v[28:31], v[128:131], v[148:151], v[28:31]
	v_mfma_f32_16x16x32_bf16 v[24:27], v[128:131], v[152:155], v[24:27]
	v_mfma_f32_16x16x32_bf16 v[20:23], v[128:131], v[156:159], v[20:23]
	v_mfma_f32_16x16x32_bf16 v[16:19], v[128:131], v[160:163], v[16:19]
	s_mov_b32 s3, 0x10000
	v_lshl_or_b32 v38, s17, 11, v45
	v_add_u32_e32 v38, s16, v38
	v_ashrrev_i32_e32 v39, 31, v38
	v_lshlrev_b64 v[40:41], 10, v[38:39]
	v_lshl_add_u64 v[40:41], v[32:33], 0, v[40:41]
	s_barrier
	global_store_dwordx4 v[40:41], v[28:31], off
	s_add_i32 s54, s54, s100
	s_cmp_gt_i32 s54, s101
	v_add_u32_e32 v28, 0x200, v38
	v_ashrrev_i32_e32 v29, 31, v28
	v_lshlrev_b64 v[28:29], 10, v[28:29]
	v_lshl_add_u64 v[28:29], v[32:33], 0, v[28:29]
	global_store_dwordx4 v[28:29], v[24:27], off
	s_nop 1
	v_add_u32_e32 v24, 0x400, v38
	v_ashrrev_i32_e32 v25, 31, v24
	v_lshlrev_b64 v[24:25], 10, v[24:25]
	v_lshl_add_u64 v[24:25], v[32:33], 0, v[24:25]
	global_store_dwordx4 v[24:25], v[20:23], off
	s_nop 1
	v_add_u32_e32 v20, 0x600, v38
	v_ashrrev_i32_e32 v21, 31, v20
	v_lshlrev_b64 v[20:21], 10, v[20:21]
	v_lshl_add_u64 v[20:21], v[32:33], 0, v[20:21]
	global_store_dwordx4 v[20:21], v[16:19], off
	global_store_dwordx4 v[40:41], v[12:15], off offset:64
	global_store_dwordx4 v[28:29], v[8:11], off offset:64
	global_store_dwordx4 v[24:25], v[4:7], off offset:64
	global_store_dwordx4 v[20:21], v[0:3], off offset:64
	s_cbranch_scc0 .LBB0_603

; __global__ void __launch_bounds__(NTHREADS) mega_fwd(Params P) {
	.amdhsa_kernel _Z8mega_fwd6Params
		.amdhsa_group_segment_fixed_size 0
		.amdhsa_private_segment_fixed_size 0
		.amdhsa_kernarg_size 488
		.amdhsa_user_sgpr_count 2
		.amdhsa_user_sgpr_dispatch_ptr 0
		.amdhsa_user_sgpr_queue_ptr 0
		.amdhsa_user_sgpr_kernarg_segment_ptr 1
		.amdhsa_user_sgpr_dispatch_id 0
		.amdhsa_user_sgpr_kernarg_preload_length 0
		.amdhsa_user_sgpr_kernarg_preload_offset 0
		.amdhsa_user_sgpr_private_segment_size 0
		.amdhsa_uses_dynamic_stack 0
		.amdhsa_enable_private_segment 0
		.amdhsa_system_sgpr_workgroup_id_x 1
		.amdhsa_system_sgpr_workgroup_id_y 0
		.amdhsa_system_sgpr_workgroup_id_z 0
		.amdhsa_system_sgpr_workgroup_info 0
		.amdhsa_system_vgpr_workitem_id 2
		.amdhsa_next_free_vgpr 256
		.amdhsa_next_free_sgpr 102
		.amdhsa_accum_offset 256
		.amdhsa_reserve_vcc 1
		.amdhsa_float_round_mode_32 0
		.amdhsa_float_round_mode_16_64 0
		.amdhsa_float_denorm_mode_32 3
		.amdhsa_float_denorm_mode_16_64 3
		.amdhsa_dx10_clamp 1
		.amdhsa_ieee_mode 1
		.amdhsa_fp16_overflow 0
		.amdhsa_tg_split 0
		.amdhsa_exception_fp_ieee_invalid_op 0
		.amdhsa_exception_fp_denorm_src 0
		.amdhsa_exception_fp_ieee_div_zero 0
		.amdhsa_exception_fp_ieee_overflow 0
		.amdhsa_exception_fp_ieee_underflow 0
		.amdhsa_exception_fp_ieee_inexact 0
		.amdhsa_exception_int_div_zero 0
	.end_amdhsa_kernel

; __global__ void __launch_bounds__(NTHREADS) mega_fwd(Params P) {
.Lfunc_end0:
	.size	_Z8mega_fwd6Params, .Lfunc_end0-_Z8mega_fwd6Params
	.set _Z8mega_fwd6Params.num_vgpr, 256
	.set _Z8mega_fwd6Params.num_agpr, 0
	.set _Z8mega_fwd6Params.numbered_sgpr, 102
	.set _Z8mega_fwd6Params.num_named_barrier, 0
	.set _Z8mega_fwd6Params.private_seg_size, 0
	.set _Z8mega_fwd6Params.uses_vcc, 1
	.set _Z8mega_fwd6Params.uses_flat_scratch, 0
	.set _Z8mega_fwd6Params.has_dyn_sized_stack, 0
	.set _Z8mega_fwd6Params.has_recursion, 0
	.set _Z8mega_fwd6Params.has_indirect_call, 0

; __global__ void __launch_bounds__(NTHREADS) mega_fwd(Params P) {
amdhsa.kernels:
  - .agpr_count:     0
    .args:
      - .offset:         0
        .size:           232
        .value_kind:     by_value
      - .offset:         232
        .size:           4
        .value_kind:     hidden_block_count_x
      - .offset:         236
        .size:           4
        .value_kind:     hidden_block_count_y
      - .offset:         240
        .size:           4
        .value_kind:     hidden_block_count_z
      - .offset:         244
        .size:           2
        .value_kind:     hidden_group_size_x
      - .offset:         246
        .size:           2
        .value_kind:     hidden_group_size_y
      - .offset:         248
        .size:           2
        .value_kind:     hidden_group_size_z
      - .offset:         250
        .size:           2
        .value_kind:     hidden_remainder_x
      - .offset:         252
        .size:           2
        .value_kind:     hidden_remainder_y
      - .offset:         254
        .size:           2
        .value_kind:     hidden_remainder_z
      - .offset:         272
        .size:           8
        .value_kind:     hidden_global_offset_x
      - .offset:         280
        .size:           8
        .value_kind:     hidden_global_offset_y
      - .offset:         288
        .size:           8
        .value_kind:     hidden_global_offset_z
      - .offset:         296
        .size:           2
        .value_kind:     hidden_grid_dims
      - .offset:         320
        .size:           8
        .value_kind:     hidden_multigrid_sync_arg
      - .offset:         352
        .size:           4
        .value_kind:     hidden_dynamic_lds_size
    .group_segment_fixed_size: 0
    .kernarg_segment_align: 8
    .kernarg_segment_size: 488
    .language:       OpenCL C
    .language_version:
      - 2
      - 0
    .max_flat_workgroup_size: 512
    .name:           _Z8mega_fwd6Params
    .private_segment_fixed_size: 0
    .sgpr_count:     108
    .sgpr_spill_count: 309
    .symbol:         _Z8mega_fwd6Params.kd
    .uniform_work_group_size: 1
    .uses_dynamic_stack: false
    .vgpr_count:     256
    .vgpr_spill_count: 0
    .wavefront_size: 64
